# baseline (speedup 1.0000x reference)
.LBB0_528:
	s_cmpk_gt_i32 s16, 0xff
	s_mov_b64 s[4:5], -1
	s_cbranch_scc1 .LBB0_522
	s_ashr_i32 s4, s16, 31
	s_lshr_b32 s4, s4, 26
	s_add_i32 s4, s16, s4
	s_andn2_b32 s4, s4, 63
	s_sub_i32 s5, s16, s4
	s_ashr_i32 s16, s5, 3
	s_lshl_b32 s5, s5, 3
	s_and_b32 s5, s5, 56
	s_or_b32 s4, s4, s5
	v_mov_b32_e32 v1, v170
	s_barrier
	s_or_b32 s4, s4, s18
	s_lshl_b32 s4, s4, 8
	v_lshlrev_b32_e32 v145, 4, v1
	v_bfe_u32 v35, v1, 2, 4
	v_ashrrev_i32_e32 v14, 2, v1
	v_add_u32_e32 v37, 0x1000, v145
	v_add_u32_e32 v38, 0x2000, v145
	v_add_u32_e32 v40, 0x3000, v145
	v_or_b32_e32 v12, s4, v35
	v_and_b32_e32 v6, -16, v14
	v_ashrrev_i32_e32 v19, 6, v37
	v_ashrrev_i32_e32 v10, 6, v38
	v_ashrrev_i32_e32 v13, 6, v40
	v_and_b32_e32 v34, 32, v1
	v_add_u32_e32 v6, v12, v6
	v_and_b32_e32 v8, -16, v19
	v_and_b32_e32 v39, -16, v10
	v_and_b32_e32 v41, -16, v13
	v_bitop3_b32 v2, v145, v34, 48 bitop3:0x6c
	v_mov_b32_e32 v3, v0
	v_ashrrev_i32_e32 v7, 31, v6
	v_add_u32_e32 v8, v8, v12
	v_add_u32_e32 v10, v39, v12
	v_add_u32_e32 v12, v41, v12
	s_ashr_i32 s17, s16, 31
	v_lshl_add_u64 v[4:5], s[36:37], 0, v[2:3]
	v_lshlrev_b64 v[6:7], 11, v[6:7]
	v_ashrrev_i32_e32 v9, 31, v8
	v_ashrrev_i32_e32 v11, 31, v10
	v_ashrrev_i32_e32 v13, 31, v12
	v_readfirstlane_b32 s5, v145
	s_lshl_b64 s[18:19], s[16:17], 18
	v_lshrrev_b32_e32 v18, 2, v1
	v_lshl_add_u64 v[6:7], v[4:5], 0, v[6:7]
	v_lshlrev_b64 v[8:9], 11, v[8:9]
	v_lshlrev_b64 v[10:11], 11, v[10:11]
	v_lshlrev_b64 v[12:13], 11, v[12:13]
	s_waitcnt vmcnt(0)
	s_mov_b32 m0, s5
	v_readfirstlane_b32 s5, v37
	s_add_u32 s26, s20, s18
	v_lshl_add_u64 v[8:9], v[4:5], 0, v[8:9]
	v_lshl_add_u64 v[10:11], v[4:5], 0, v[10:11]
	v_lshl_add_u64 v[4:5], v[4:5], 0, v[12:13]
	v_bfi_b32 v12, 15, v18, v14
	s_mov_b32 m0, s5
	v_readfirstlane_b32 s5, v38
	s_addc_u32 s27, s21, s19
	v_ashrrev_i32_e32 v13, 31, v12
	v_bfi_b32 v18, -16, v19, v18
	v_add_u32_e32 v42, 0x4000, v145
	s_mov_b32 m0, s5
	v_readfirstlane_b32 s5, v40
	v_lshl_add_u64 v[2:3], s[26:27], 0, v[2:3]
	v_lshlrev_b64 v[14:15], 11, v[12:13]
	v_ashrrev_i32_e32 v19, 31, v18
	v_add_u32_e32 v43, 0x5000, v145
	s_mov_b32 m0, s5
	v_readfirstlane_b32 s5, v42
	v_lshl_add_u64 v[16:17], v[2:3], 0, v[14:15]
	v_lshlrev_b64 v[20:21], 11, v[18:19]
	v_add_u32_e32 v44, 0x6000, v145
	s_mov_b32 m0, s5
	v_readfirstlane_b32 s5, v43
	v_and_b32_e32 v142, 15, v1
	v_lshl_add_u64 v[2:3], v[2:3], 0, v[20:21]
	v_bfe_u32 v143, v1, 4, 2
	v_lshlrev_b32_e32 v19, 6, v1
	v_lshlrev_b32_e32 v22, 2, v1
	v_add_u32_e32 v45, 0x7000, v145
	s_mov_b32 m0, s5
	v_readfirstlane_b32 s5, v44
	v_lshlrev_b32_e32 v13, 4, v143
	v_and_b32_e32 v24, 0x3c0, v19
	v_lshlrev_b32_e32 v25, 6, v142
	v_and_b32_e32 v26, 32, v22
	v_lshl_add_u64 v[22:23], v[6:7], 0, 64
	v_add_u32_e32 v46, 0x8000, v145
	s_mov_b32 m0, s5
	v_readfirstlane_b32 s5, v45
	v_add_u32_e32 v47, 0x9000, v145
	v_bitop3_b32 v149, v13, v26, v24 bitop3:0x36
	v_bitop3_b32 v144, v13, v26, v25 bitop3:0x36
	v_lshl_add_u64 v[24:25], v[8:9], 0, 64
	s_mov_b32 m0, s5
	v_readfirstlane_b32 s5, v46
	v_add_u32_e32 v48, 0xa000, v145
	v_lshl_add_u64 v[26:27], v[10:11], 0, 64
	s_mov_b32 m0, s5
	v_readfirstlane_b32 s5, v47
	v_add_u32_e32 v49, 0xb000, v145
	v_lshl_add_u64 v[28:29], v[4:5], 0, 64
	s_mov_b32 m0, s5
	v_readfirstlane_b32 s5, v48
	v_lshl_add_u64 v[30:31], v[16:17], 0, 64
	s_mov_b32 m0, s5
	v_readfirstlane_b32 s5, v49
	v_lshl_add_u64 v[32:33], v[2:3], 0, 64
	s_mov_b32 m0, s5
	v_and_b32_e32 v36, 48, v145
	v_lshl_add_u64 v[2:3], s[18:19], 0, v[20:21]
	v_bitop3_b32 v2, v2, v36, v34 bitop3:0xf6
	v_lshl_add_u64 v[130:131], s[12:13], 0, v[2:3]
	v_lshl_add_u64 v[2:3], s[18:19], 0, v[14:15]
	v_bitop3_b32 v2, v2, v36, v34 bitop3:0xf6
	v_lshl_add_u64 v[132:133], s[12:13], 0, v[2:3]
	v_add_u32_e32 v2, s4, v41
	v_or_b32_e32 v2, v2, v35
	v_ashrrev_i32_e32 v3, 31, v2
	v_lshlrev_b64 v[2:3], 11, v[2:3]
	v_bitop3_b32 v2, v2, v36, v34 bitop3:0xf6
	v_lshl_add_u64 v[134:135], s[14:15], 0, v[2:3]
	v_add_u32_e32 v2, s4, v39
	v_or_b32_e32 v2, v2, v35
	v_ashrrev_i32_e32 v3, 31, v2
	v_lshlrev_b64 v[2:3], 11, v[2:3]
	v_bitop3_b32 v2, v2, v36, v34 bitop3:0xf6
	v_lshl_add_u64 v[136:137], s[14:15], 0, v[2:3]
	v_add_u32_e32 v2, s4, v18
	v_ashrrev_i32_e32 v3, 31, v2
	v_lshlrev_b64 v[2:3], 11, v[2:3]
	v_bitop3_b32 v2, v2, v36, v34 bitop3:0xf6
	v_lshl_add_u64 v[138:139], s[14:15], 0, v[2:3]
	v_add_u32_e32 v2, s4, v12
	v_ashrrev_i32_e32 v3, 31, v2
	v_lshlrev_b64 v[2:3], 11, v[2:3]
	v_bitop3_b32 v2, v2, v36, v34 bitop3:0xf6
	v_lshl_add_u64 v[140:141], s[14:15], 0, v[2:3]
	v_mov_b32_e32 v2, 0
	v_and_b32_e32 v147, 0xfffff000, v19
	s_mov_b32 s5, 0
	s_mov_b64 s[18:19], 0
	v_mov_b32_e32 v3, v2
	v_mov_b32_e32 v4, v2
	v_mov_b32_e32 v5, v2
	v_mov_b32_e32 v6, v2
	v_mov_b32_e32 v7, v2
	v_mov_b32_e32 v8, v2
	v_mov_b32_e32 v9, v2
	v_mov_b32_e32 v10, v2
	v_mov_b32_e32 v11, v2
	v_mov_b32_e32 v12, v2
	v_mov_b32_e32 v13, v2
	v_mov_b32_e32 v14, v2
	v_mov_b32_e32 v15, v2
	v_mov_b32_e32 v16, v2
	v_mov_b32_e32 v17, v2
	v_mov_b32_e32 v18, v2
	v_mov_b32_e32 v19, v2
	v_mov_b32_e32 v20, v2
	v_mov_b32_e32 v21, v2
	v_mov_b32_e32 v26, v2
	v_mov_b32_e32 v27, v2
	v_mov_b32_e32 v28, v2
	v_mov_b32_e32 v29, v2
	v_mov_b32_e32 v38, v2
	v_mov_b32_e32 v39, v2
	v_mov_b32_e32 v40, v2
	v_mov_b32_e32 v41, v2
	v_mov_b32_e32 v54, v2
	v_mov_b32_e32 v55, v2
	v_mov_b32_e32 v56, v2
	v_mov_b32_e32 v57, v2
	v_mov_b32_e32 v22, v2
	v_mov_b32_e32 v23, v2
	v_mov_b32_e32 v24, v2
	v_mov_b32_e32 v25, v2
	v_mov_b32_e32 v30, v2
	v_mov_b32_e32 v31, v2
	v_mov_b32_e32 v32, v2
	v_mov_b32_e32 v33, v2
	v_mov_b32_e32 v34, v2
	v_mov_b32_e32 v35, v2
	v_mov_b32_e32 v36, v2
	v_mov_b32_e32 v37, v2
	v_mov_b32_e32 v42, v2
	v_mov_b32_e32 v43, v2
	v_mov_b32_e32 v44, v2
	v_mov_b32_e32 v45, v2
	v_mov_b32_e32 v46, v2
	v_mov_b32_e32 v47, v2
	v_mov_b32_e32 v48, v2
	v_mov_b32_e32 v49, v2
	v_mov_b32_e32 v58, v2
	v_mov_b32_e32 v59, v2
	v_mov_b32_e32 v60, v2
	v_mov_b32_e32 v61, v2
	v_mov_b32_e32 v70, v2
	v_mov_b32_e32 v71, v2
	v_mov_b32_e32 v72, v2
	v_mov_b32_e32 v73, v2
	v_mov_b32_e32 v86, v2
	v_mov_b32_e32 v87, v2
	v_mov_b32_e32 v88, v2
	v_mov_b32_e32 v89, v2
	v_mov_b32_e32 v50, v2
	v_mov_b32_e32 v51, v2
	v_mov_b32_e32 v52, v2
	v_mov_b32_e32 v53, v2
	v_mov_b32_e32 v62, v2
	v_mov_b32_e32 v63, v2
	v_mov_b32_e32 v64, v2
	v_mov_b32_e32 v65, v2
	v_mov_b32_e32 v66, v2
	v_mov_b32_e32 v67, v2
	v_mov_b32_e32 v68, v2
	v_mov_b32_e32 v69, v2
	v_mov_b32_e32 v74, v2
	v_mov_b32_e32 v75, v2
	v_mov_b32_e32 v76, v2
	v_mov_b32_e32 v77, v2
	v_mov_b32_e32 v78, v2
	v_mov_b32_e32 v79, v2
	v_mov_b32_e32 v80, v2
	v_mov_b32_e32 v81, v2
	v_mov_b32_e32 v90, v2
	v_mov_b32_e32 v91, v2
	v_mov_b32_e32 v92, v2
	v_mov_b32_e32 v93, v2
	v_mov_b32_e32 v102, v2
	v_mov_b32_e32 v103, v2
	v_mov_b32_e32 v104, v2
	v_mov_b32_e32 v105, v2
	v_mov_b32_e32 v114, v2
	v_mov_b32_e32 v115, v2
	v_mov_b32_e32 v116, v2
	v_mov_b32_e32 v117, v2
	v_mov_b32_e32 v82, v2
	v_mov_b32_e32 v83, v2
	v_mov_b32_e32 v84, v2
	v_mov_b32_e32 v85, v2
	v_mov_b32_e32 v94, v2
	v_mov_b32_e32 v95, v2
	v_mov_b32_e32 v96, v2
	v_mov_b32_e32 v97, v2
	v_mov_b32_e32 v98, v2
	v_mov_b32_e32 v99, v2
	v_mov_b32_e32 v100, v2
	v_mov_b32_e32 v101, v2
	v_mov_b32_e32 v106, v2
	v_mov_b32_e32 v107, v2
	v_mov_b32_e32 v108, v2
	v_mov_b32_e32 v109, v2
	v_mov_b32_e32 v110, v2
	v_mov_b32_e32 v111, v2
	v_mov_b32_e32 v112, v2
	v_mov_b32_e32 v113, v2
	v_mov_b32_e32 v118, v2
	v_mov_b32_e32 v119, v2
	v_mov_b32_e32 v120, v2
	v_mov_b32_e32 v121, v2
	v_mov_b32_e32 v122, v2
	v_mov_b32_e32 v123, v2
	v_mov_b32_e32 v124, v2
	v_mov_b32_e32 v125, v2
	v_mov_b32_e32 v126, v2
	v_mov_b32_e32 v127, v2
	v_mov_b32_e32 v128, v2
	v_mov_b32_e32 v129, v2
	v_and_b32_e32 v154, 63, v170
	v_lshrrev_b32_e32 v155, 3, v154
	v_and_b32_e32 v156, 7, v154
	v_xor_b32_e32 v156, v156, v155
	v_lshrrev_b32_e32 v157, 6, v170
	v_lshl_add_u32 v158, v157, 6, v155
	v_add_u32_e32 v158, s4, v158
	v_mul_u32_u24_e32 v224, 0x800, v158
	v_lshl_add_u32 v224, v156, 4, v224
	v_lshl_add_u32 v158, v157, 5, v155
	v_mul_u32_u24_e32 v225, 0x800, v158
	v_lshl_add_u32 v225, v156, 4, v225
	v_and_b32_e32 v155, 15, v154
	v_lshrrev_b32_e32 v156, 4, v154
	v_and_b32_e32 v158, 7, v155
	v_xor_b32_e32 v156, v156, v158
	v_lshlrev_b32_e32 v156, 4, v156
	v_lshl_add_u32 v229, v155, 7, v156
	v_lshl_add_u32 v227, v157, 13, v229
	v_xor_b32_e32 v228, 64, v227
	v_add_u32_e32 v229, 0xc000, v229
	v_xor_b32_e32 v230, 64, v229
	s_mov_b32 s18, s36
	s_mov_b32 s19, s37
	s_sub_u32 s32, s26, s36
	v_add_u32_e32 v225, s32, v225
	s_mov_b32 s25, 0
	v_readfirstlane_b32 s32, v145
	s_lshl_b32 m0, s32, 3
	v_mov_b32_e32 v226, v224
	global_load_lds_dwordx4 v226, s[18:19]
	s_add_u32 m0, m0, 0x400
	v_add_u32_e32 v226, 0x4000, v224
	global_load_lds_dwordx4 v226, s[18:19]
	s_add_u32 m0, m0, 0x400
	v_add_u32_e32 v226, 0x8000, v224
	global_load_lds_dwordx4 v226, s[18:19]
	s_add_u32 m0, m0, 0x400
	v_add_u32_e32 v226, 0xc000, v224
	global_load_lds_dwordx4 v226, s[18:19]
	s_add_u32 m0, m0, 0x400
	v_add_u32_e32 v226, 0x10000, v224
	global_load_lds_dwordx4 v226, s[18:19]
	s_add_u32 m0, m0, 0x400
	v_add_u32_e32 v226, 0x14000, v224
	global_load_lds_dwordx4 v226, s[18:19]
	s_add_u32 m0, m0, 0x400
	v_add_u32_e32 v226, 0x18000, v224
	global_load_lds_dwordx4 v226, s[18:19]
	s_add_u32 m0, m0, 0x400
	v_add_u32_e32 v226, 0x1c000, v224
	global_load_lds_dwordx4 v226, s[18:19]
	v_readfirstlane_b32 s32, v145
	s_lshl_b32 s32, s32, 2
	s_add_u32 m0, s32, 0xc000
	v_mov_b32_e32 v226, v225
	global_load_lds_dwordx4 v226, s[18:19]
	s_add_u32 m0, m0, 0x400
	v_add_u32_e32 v226, 0x4000, v225
	global_load_lds_dwordx4 v226, s[18:19]
	s_add_u32 m0, m0, 0x400
	v_add_u32_e32 v226, 0x8000, v225
	global_load_lds_dwordx4 v226, s[18:19]
	s_add_u32 m0, m0, 0x400
	v_add_u32_e32 v226, 0xc000, v225
	global_load_lds_dwordx4 v226, s[18:19]
.Lbk64_530:
	s_waitcnt vmcnt(0)
	s_barrier
	ds_read_b128 v[192:195], v227
	ds_read_b128 v[196:199], v228
	ds_read_b128 v[200:203], v227 offset:2048
	ds_read_b128 v[204:207], v228 offset:2048
	ds_read_b128 v[208:211], v227 offset:4096
	ds_read_b128 v[212:215], v228 offset:4096
	ds_read_b128 v[216:219], v227 offset:6144
	ds_read_b128 v[220:223], v228 offset:6144
	s_add_u32 s18, s18, 0x80
	s_addc_u32 s19, s19, 0
	s_waitcnt lgkmcnt(0)
	s_barrier
	ds_read_b128 v[154:157], v229 offset:0
	ds_read_b128 v[158:161], v230 offset:0
	ds_read_b128 v[162:165], v229 offset:2048
	ds_read_b128 v[166:169], v230 offset:2048
	s_waitcnt lgkmcnt(2)
	v_mfma_f32_16x16x32_bf16 v[126:129], v[192:195], v[154:157], v[126:129]
	v_mfma_f32_16x16x32_bf16 v[114:117], v[200:203], v[154:157], v[114:117]
	v_mfma_f32_16x16x32_bf16 v[86:89], v[208:211], v[154:157], v[86:89]
	v_mfma_f32_16x16x32_bf16 v[54:57], v[216:219], v[154:157], v[54:57]
	v_readfirstlane_b32 s32, v145
	s_lshl_b32 m0, s32, 3
	v_mov_b32_e32 v226, v224
	global_load_lds_dwordx4 v226, s[18:19]
	v_mfma_f32_16x16x32_bf16 v[126:129], v[196:199], v[158:161], v[126:129]
	v_mfma_f32_16x16x32_bf16 v[114:117], v[204:207], v[158:161], v[114:117]
	v_mfma_f32_16x16x32_bf16 v[86:89], v[212:215], v[158:161], v[86:89]
	v_mfma_f32_16x16x32_bf16 v[54:57], v[220:223], v[158:161], v[54:57]
	s_add_u32 m0, m0, 0x400
	v_add_u32_e32 v226, 0x4000, v224
	global_load_lds_dwordx4 v226, s[18:19]
	ds_read_b128 v[154:157], v229 offset:4096
	ds_read_b128 v[158:161], v230 offset:4096
	s_waitcnt lgkmcnt(2)
	v_mfma_f32_16x16x32_bf16 v[122:125], v[192:195], v[162:165], v[122:125]
	v_mfma_f32_16x16x32_bf16 v[102:105], v[200:203], v[162:165], v[102:105]
	v_mfma_f32_16x16x32_bf16 v[70:73], v[208:211], v[162:165], v[70:73]
	v_mfma_f32_16x16x32_bf16 v[38:41], v[216:219], v[162:165], v[38:41]
	s_add_u32 m0, m0, 0x400
	v_add_u32_e32 v226, 0x8000, v224
	global_load_lds_dwordx4 v226, s[18:19]
	v_mfma_f32_16x16x32_bf16 v[122:125], v[196:199], v[166:169], v[122:125]
	v_mfma_f32_16x16x32_bf16 v[102:105], v[204:207], v[166:169], v[102:105]
	v_mfma_f32_16x16x32_bf16 v[70:73], v[212:215], v[166:169], v[70:73]
	v_mfma_f32_16x16x32_bf16 v[38:41], v[220:223], v[166:169], v[38:41]
	s_add_u32 m0, m0, 0x400
	v_add_u32_e32 v226, 0xc000, v224
	global_load_lds_dwordx4 v226, s[18:19]
	ds_read_b128 v[162:165], v229 offset:6144
	ds_read_b128 v[166:169], v230 offset:6144
	s_waitcnt lgkmcnt(2)
	v_mfma_f32_16x16x32_bf16 v[118:121], v[192:195], v[154:157], v[118:121]
	v_mfma_f32_16x16x32_bf16 v[90:93], v[200:203], v[154:157], v[90:93]
	v_mfma_f32_16x16x32_bf16 v[58:61], v[208:211], v[154:157], v[58:61]
	v_mfma_f32_16x16x32_bf16 v[26:29], v[216:219], v[154:157], v[26:29]
	s_add_u32 m0, m0, 0x400
	v_add_u32_e32 v226, 0x10000, v224
	global_load_lds_dwordx4 v226, s[18:19]
	v_mfma_f32_16x16x32_bf16 v[118:121], v[196:199], v[158:161], v[118:121]
	v_mfma_f32_16x16x32_bf16 v[90:93], v[204:207], v[158:161], v[90:93]
	v_mfma_f32_16x16x32_bf16 v[58:61], v[212:215], v[158:161], v[58:61]
	v_mfma_f32_16x16x32_bf16 v[26:29], v[220:223], v[158:161], v[26:29]
	s_add_u32 m0, m0, 0x400
	v_add_u32_e32 v226, 0x14000, v224
	global_load_lds_dwordx4 v226, s[18:19]
	ds_read_b128 v[154:157], v229 offset:8192
	ds_read_b128 v[158:161], v230 offset:8192
	s_waitcnt lgkmcnt(2)
	v_mfma_f32_16x16x32_bf16 v[110:113], v[192:195], v[162:165], v[110:113]
	v_mfma_f32_16x16x32_bf16 v[78:81], v[200:203], v[162:165], v[78:81]
	v_mfma_f32_16x16x32_bf16 v[46:49], v[208:211], v[162:165], v[46:49]
	v_mfma_f32_16x16x32_bf16 v[18:21], v[216:219], v[162:165], v[18:21]
	s_add_u32 m0, m0, 0x400
	v_add_u32_e32 v226, 0x18000, v224
	global_load_lds_dwordx4 v226, s[18:19]
	v_mfma_f32_16x16x32_bf16 v[110:113], v[196:199], v[166:169], v[110:113]
	v_mfma_f32_16x16x32_bf16 v[78:81], v[204:207], v[166:169], v[78:81]
	v_mfma_f32_16x16x32_bf16 v[46:49], v[212:215], v[166:169], v[46:49]
	v_mfma_f32_16x16x32_bf16 v[18:21], v[220:223], v[166:169], v[18:21]
	s_add_u32 m0, m0, 0x400
	v_add_u32_e32 v226, 0x1c000, v224
	global_load_lds_dwordx4 v226, s[18:19]
	ds_read_b128 v[162:165], v229 offset:10240
	ds_read_b128 v[166:169], v230 offset:10240
	s_waitcnt lgkmcnt(2)
	v_mfma_f32_16x16x32_bf16 v[106:109], v[192:195], v[154:157], v[106:109]
	v_mfma_f32_16x16x32_bf16 v[74:77], v[200:203], v[154:157], v[74:77]
	v_mfma_f32_16x16x32_bf16 v[42:45], v[208:211], v[154:157], v[42:45]
	v_mfma_f32_16x16x32_bf16 v[14:17], v[216:219], v[154:157], v[14:17]
	s_add_u32 m0, s25, 16
	s_and_b32 m0, m0, 1
	s_lshl_b32 m0, m0, 14
	s_add_u32 m0, m0, 0x8000
	v_readfirstlane_b32 s32, v145
	s_lshl_b32 s32, s32, 2
	s_add_u32 m0, m0, s32
	v_mov_b32_e32 v226, v225
	global_load_lds_dwordx4 v226, s[18:19]
	v_mfma_f32_16x16x32_bf16 v[106:109], v[196:199], v[158:161], v[106:109]
	v_mfma_f32_16x16x32_bf16 v[74:77], v[204:207], v[158:161], v[74:77]
	v_mfma_f32_16x16x32_bf16 v[42:45], v[212:215], v[158:161], v[42:45]
	v_mfma_f32_16x16x32_bf16 v[14:17], v[220:223], v[158:161], v[14:17]
	s_add_u32 m0, m0, 0x400
	v_add_u32_e32 v226, 0x4000, v225
	global_load_lds_dwordx4 v226, s[18:19]
	ds_read_b128 v[154:157], v229 offset:12288
	ds_read_b128 v[158:161], v230 offset:12288
	s_waitcnt lgkmcnt(2)
	v_mfma_f32_16x16x32_bf16 v[98:101], v[192:195], v[162:165], v[98:101]
	v_mfma_f32_16x16x32_bf16 v[66:69], v[200:203], v[162:165], v[66:69]
	v_mfma_f32_16x16x32_bf16 v[34:37], v[208:211], v[162:165], v[34:37]
	v_mfma_f32_16x16x32_bf16 v[10:13], v[216:219], v[162:165], v[10:13]
	s_add_u32 m0, m0, 0x400
	v_add_u32_e32 v226, 0x8000, v225
	global_load_lds_dwordx4 v226, s[18:19]
	v_mfma_f32_16x16x32_bf16 v[98:101], v[196:199], v[166:169], v[98:101]
	v_mfma_f32_16x16x32_bf16 v[66:69], v[204:207], v[166:169], v[66:69]
	v_mfma_f32_16x16x32_bf16 v[34:37], v[212:215], v[166:169], v[34:37]
	v_mfma_f32_16x16x32_bf16 v[10:13], v[220:223], v[166:169], v[10:13]
	s_add_u32 m0, m0, 0x400
	v_add_u32_e32 v226, 0xc000, v225
	global_load_lds_dwordx4 v226, s[18:19]
	ds_read_b128 v[162:165], v229 offset:14336
	ds_read_b128 v[166:169], v230 offset:14336
	s_waitcnt lgkmcnt(2)
	v_mfma_f32_16x16x32_bf16 v[94:97], v[192:195], v[154:157], v[94:97]
	v_mfma_f32_16x16x32_bf16 v[62:65], v[200:203], v[154:157], v[62:65]
	v_mfma_f32_16x16x32_bf16 v[30:33], v[208:211], v[154:157], v[30:33]
	v_mfma_f32_16x16x32_bf16 v[6:9], v[216:219], v[154:157], v[6:9]
	v_mfma_f32_16x16x32_bf16 v[94:97], v[196:199], v[158:161], v[94:97]
	v_mfma_f32_16x16x32_bf16 v[62:65], v[204:207], v[158:161], v[62:65]
	v_mfma_f32_16x16x32_bf16 v[30:33], v[212:215], v[158:161], v[30:33]
	v_mfma_f32_16x16x32_bf16 v[6:9], v[220:223], v[158:161], v[6:9]
	s_waitcnt lgkmcnt(0)
	v_mfma_f32_16x16x32_bf16 v[82:85], v[192:195], v[162:165], v[82:85]
	v_mfma_f32_16x16x32_bf16 v[50:53], v[200:203], v[162:165], v[50:53]
	v_mfma_f32_16x16x32_bf16 v[22:25], v[208:211], v[162:165], v[22:25]
	v_mfma_f32_16x16x32_bf16 v[2:5], v[216:219], v[162:165], v[2:5]
	v_mfma_f32_16x16x32_bf16 v[82:85], v[196:199], v[166:169], v[82:85]
	v_mfma_f32_16x16x32_bf16 v[50:53], v[204:207], v[166:169], v[50:53]
	v_mfma_f32_16x16x32_bf16 v[22:25], v[212:215], v[166:169], v[22:25]
	v_mfma_f32_16x16x32_bf16 v[2:5], v[220:223], v[166:169], v[2:5]
	v_xor_b32_e32 v229, 0x4000, v229
	v_xor_b32_e32 v230, 0x4000, v230
	s_add_i32 s25, s25, 1
	s_cmp_lg_u32 s25, 14
	s_cbranch_scc1 .Lbk64_530
	s_waitcnt vmcnt(0)
	s_barrier
	ds_read_b128 v[192:195], v227
	ds_read_b128 v[196:199], v228
	ds_read_b128 v[200:203], v227 offset:2048
	ds_read_b128 v[204:207], v228 offset:2048
	ds_read_b128 v[208:211], v227 offset:4096
	ds_read_b128 v[212:215], v228 offset:4096
	ds_read_b128 v[216:219], v227 offset:6144
	ds_read_b128 v[220:223], v228 offset:6144
	s_waitcnt lgkmcnt(0)
	s_barrier
	ds_read_b128 v[154:157], v229 offset:0
	ds_read_b128 v[158:161], v230 offset:0
	ds_read_b128 v[162:165], v229 offset:2048
	ds_read_b128 v[166:169], v230 offset:2048
	s_waitcnt lgkmcnt(2)
	v_mfma_f32_16x16x32_bf16 v[126:129], v[192:195], v[154:157], v[126:129]
	v_mfma_f32_16x16x32_bf16 v[114:117], v[200:203], v[154:157], v[114:117]
	v_mfma_f32_16x16x32_bf16 v[86:89], v[208:211], v[154:157], v[86:89]
	v_mfma_f32_16x16x32_bf16 v[54:57], v[216:219], v[154:157], v[54:57]
	s_mov_b64 s[18:19], 0x700
	v_readfirstlane_b32 s32, v145
	s_mov_b32 m0, s32
	v_lshl_add_u64 v[224:225], v[140:141], 0, s[18:19]
	global_load_lds_dwordx4 v[224:225], off
	v_mfma_f32_16x16x32_bf16 v[126:129], v[196:199], v[158:161], v[126:129]
	v_mfma_f32_16x16x32_bf16 v[114:117], v[204:207], v[158:161], v[114:117]
	v_mfma_f32_16x16x32_bf16 v[86:89], v[212:215], v[158:161], v[86:89]
	v_mfma_f32_16x16x32_bf16 v[54:57], v[220:223], v[158:161], v[54:57]
	s_add_u32 m0, m0, 0x1000
	v_lshl_add_u64 v[224:225], v[138:139], 0, s[18:19]
	global_load_lds_dwordx4 v[224:225], off
	ds_read_b128 v[154:157], v229 offset:4096
	ds_read_b128 v[158:161], v230 offset:4096
	s_waitcnt lgkmcnt(2)
	v_mfma_f32_16x16x32_bf16 v[122:125], v[192:195], v[162:165], v[122:125]
	v_mfma_f32_16x16x32_bf16 v[102:105], v[200:203], v[162:165], v[102:105]
	v_mfma_f32_16x16x32_bf16 v[70:73], v[208:211], v[162:165], v[70:73]
	v_mfma_f32_16x16x32_bf16 v[38:41], v[216:219], v[162:165], v[38:41]
	s_add_u32 m0, m0, 0x1000
	v_lshl_add_u64 v[224:225], v[136:137], 0, s[18:19]
	global_load_lds_dwordx4 v[224:225], off
	v_mfma_f32_16x16x32_bf16 v[122:125], v[196:199], v[166:169], v[122:125]
	v_mfma_f32_16x16x32_bf16 v[102:105], v[204:207], v[166:169], v[102:105]
	v_mfma_f32_16x16x32_bf16 v[70:73], v[212:215], v[166:169], v[70:73]
	v_mfma_f32_16x16x32_bf16 v[38:41], v[220:223], v[166:169], v[38:41]
	s_add_u32 m0, m0, 0x1000
	v_lshl_add_u64 v[224:225], v[134:135], 0, s[18:19]
	global_load_lds_dwordx4 v[224:225], off
	ds_read_b128 v[162:165], v229 offset:6144
	ds_read_b128 v[166:169], v230 offset:6144
	s_waitcnt lgkmcnt(2)
	v_mfma_f32_16x16x32_bf16 v[118:121], v[192:195], v[154:157], v[118:121]
	v_mfma_f32_16x16x32_bf16 v[90:93], v[200:203], v[154:157], v[90:93]
	v_mfma_f32_16x16x32_bf16 v[58:61], v[208:211], v[154:157], v[58:61]
	v_mfma_f32_16x16x32_bf16 v[26:29], v[216:219], v[154:157], v[26:29]
	s_add_u32 m0, m0, 0x1000
	v_lshl_add_u64 v[224:225], v[132:133], 0, s[18:19]
	global_load_lds_dwordx4 v[224:225], off
	v_mfma_f32_16x16x32_bf16 v[118:121], v[196:199], v[158:161], v[118:121]
	v_mfma_f32_16x16x32_bf16 v[90:93], v[204:207], v[158:161], v[90:93]
	v_mfma_f32_16x16x32_bf16 v[58:61], v[212:215], v[158:161], v[58:61]
	v_mfma_f32_16x16x32_bf16 v[26:29], v[220:223], v[158:161], v[26:29]
	s_add_u32 m0, m0, 0x1000
	v_lshl_add_u64 v[224:225], v[130:131], 0, s[18:19]
	global_load_lds_dwordx4 v[224:225], off
	ds_read_b128 v[154:157], v229 offset:8192
	ds_read_b128 v[158:161], v230 offset:8192
	s_waitcnt lgkmcnt(2)
	v_mfma_f32_16x16x32_bf16 v[110:113], v[192:195], v[162:165], v[110:113]
	v_mfma_f32_16x16x32_bf16 v[78:81], v[200:203], v[162:165], v[78:81]
	v_mfma_f32_16x16x32_bf16 v[46:49], v[208:211], v[162:165], v[46:49]
	v_mfma_f32_16x16x32_bf16 v[18:21], v[216:219], v[162:165], v[18:21]
	s_mov_b64 s[18:19], 0x740
	v_readfirstlane_b32 s32, v145
	s_add_u32 m0, s32, 0x6000
	v_lshl_add_u64 v[224:225], v[140:141], 0, s[18:19]
	global_load_lds_dwordx4 v[224:225], off
	v_mfma_f32_16x16x32_bf16 v[110:113], v[196:199], v[166:169], v[110:113]
	v_mfma_f32_16x16x32_bf16 v[78:81], v[204:207], v[166:169], v[78:81]
	v_mfma_f32_16x16x32_bf16 v[46:49], v[212:215], v[166:169], v[46:49]
	v_mfma_f32_16x16x32_bf16 v[18:21], v[220:223], v[166:169], v[18:21]
	s_add_u32 m0, m0, 0x1000
	v_lshl_add_u64 v[224:225], v[138:139], 0, s[18:19]
	global_load_lds_dwordx4 v[224:225], off
	ds_read_b128 v[162:165], v229 offset:10240
	ds_read_b128 v[166:169], v230 offset:10240
	s_waitcnt lgkmcnt(2)
	v_mfma_f32_16x16x32_bf16 v[106:109], v[192:195], v[154:157], v[106:109]
	v_mfma_f32_16x16x32_bf16 v[74:77], v[200:203], v[154:157], v[74:77]
	v_mfma_f32_16x16x32_bf16 v[42:45], v[208:211], v[154:157], v[42:45]
	v_mfma_f32_16x16x32_bf16 v[14:17], v[216:219], v[154:157], v[14:17]
	s_add_u32 m0, m0, 0x1000
	v_lshl_add_u64 v[224:225], v[136:137], 0, s[18:19]
	global_load_lds_dwordx4 v[224:225], off
	v_mfma_f32_16x16x32_bf16 v[106:109], v[196:199], v[158:161], v[106:109]
	v_mfma_f32_16x16x32_bf16 v[74:77], v[204:207], v[158:161], v[74:77]
	v_mfma_f32_16x16x32_bf16 v[42:45], v[212:215], v[158:161], v[42:45]
	v_mfma_f32_16x16x32_bf16 v[14:17], v[220:223], v[158:161], v[14:17]
	s_add_u32 m0, m0, 0x1000
	v_lshl_add_u64 v[224:225], v[134:135], 0, s[18:19]
	global_load_lds_dwordx4 v[224:225], off
	ds_read_b128 v[154:157], v229 offset:12288
	ds_read_b128 v[158:161], v230 offset:12288
	s_waitcnt lgkmcnt(2)
	v_mfma_f32_16x16x32_bf16 v[98:101], v[192:195], v[162:165], v[98:101]
	v_mfma_f32_16x16x32_bf16 v[66:69], v[200:203], v[162:165], v[66:69]
	v_mfma_f32_16x16x32_bf16 v[34:37], v[208:211], v[162:165], v[34:37]
	v_mfma_f32_16x16x32_bf16 v[10:13], v[216:219], v[162:165], v[10:13]
	s_add_u32 m0, m0, 0x1000
	v_lshl_add_u64 v[224:225], v[132:133], 0, s[18:19]
	global_load_lds_dwordx4 v[224:225], off
	v_mfma_f32_16x16x32_bf16 v[98:101], v[196:199], v[166:169], v[98:101]
	v_mfma_f32_16x16x32_bf16 v[66:69], v[204:207], v[166:169], v[66:69]
	v_mfma_f32_16x16x32_bf16 v[34:37], v[212:215], v[166:169], v[34:37]
	v_mfma_f32_16x16x32_bf16 v[10:13], v[220:223], v[166:169], v[10:13]
	s_add_u32 m0, m0, 0x1000
	v_lshl_add_u64 v[224:225], v[130:131], 0, s[18:19]
	global_load_lds_dwordx4 v[224:225], off
	ds_read_b128 v[162:165], v229 offset:14336
	ds_read_b128 v[166:169], v230 offset:14336
	s_waitcnt lgkmcnt(2)
	v_mfma_f32_16x16x32_bf16 v[94:97], v[192:195], v[154:157], v[94:97]
	v_mfma_f32_16x16x32_bf16 v[62:65], v[200:203], v[154:157], v[62:65]
	v_mfma_f32_16x16x32_bf16 v[30:33], v[208:211], v[154:157], v[30:33]
	v_mfma_f32_16x16x32_bf16 v[6:9], v[216:219], v[154:157], v[6:9]
	v_mfma_f32_16x16x32_bf16 v[94:97], v[196:199], v[158:161], v[94:97]
	v_mfma_f32_16x16x32_bf16 v[62:65], v[204:207], v[158:161], v[62:65]
	v_mfma_f32_16x16x32_bf16 v[30:33], v[212:215], v[158:161], v[30:33]
	v_mfma_f32_16x16x32_bf16 v[6:9], v[220:223], v[158:161], v[6:9]
	s_waitcnt lgkmcnt(0)
	v_mfma_f32_16x16x32_bf16 v[82:85], v[192:195], v[162:165], v[82:85]
	v_mfma_f32_16x16x32_bf16 v[50:53], v[200:203], v[162:165], v[50:53]
	v_mfma_f32_16x16x32_bf16 v[22:25], v[208:211], v[162:165], v[22:25]
	v_mfma_f32_16x16x32_bf16 v[2:5], v[216:219], v[162:165], v[2:5]
	v_mfma_f32_16x16x32_bf16 v[82:85], v[196:199], v[166:169], v[82:85]
	v_mfma_f32_16x16x32_bf16 v[50:53], v[204:207], v[166:169], v[50:53]
	v_mfma_f32_16x16x32_bf16 v[22:25], v[212:215], v[166:169], v[22:25]
	v_mfma_f32_16x16x32_bf16 v[2:5], v[220:223], v[166:169], v[2:5]
	s_waitcnt vmcnt(6)
	s_barrier
	v_add_u32_e32 v145, v149, v147
	ds_read_b128 v[130:133], v145
	ds_read_b128 v[134:137], v145 offset:1024
	ds_read_b128 v[138:141], v145 offset:2048
	ds_read_b128 v[158:161], v145 offset:3072
	ds_read_b128 v[162:165], v144 offset:16384
	ds_read_b128 v[166:169], v144 offset:17408
	ds_read_b128 v[192:195], v144 offset:18432
	ds_read_b128 v[196:199], v144 offset:19456
	ds_read_b128 v[200:203], v144 offset:20480
	ds_read_b128 v[204:207], v144 offset:21504
	ds_read_b128 v[208:211], v144 offset:22528
	ds_read_b128 v[212:215], v144 offset:23552
	s_waitcnt vmcnt(0)
	s_barrier
	s_waitcnt lgkmcnt(0)
	v_mfma_f32_16x16x32_bf16 v[126:129], v[130:133], v[162:165], v[126:129]
	s_lshl_b32 s18, s16, 7
	s_ashr_i32 s19, s18, 31
	s_lshl_b64 s[18:19], s[18:19], 1
	v_mfma_f32_16x16x32_bf16 v[114:117], v[134:137], v[162:165], v[114:117]
	v_and_b32_e32 v1, 0xfffffc0, v1
	v_lshl_or_b32 v1, v143, 2, v1
	v_mul_lo_u32 v1, v1, s33
	v_mfma_f32_16x16x32_bf16 v[86:89], v[138:141], v[162:165], v[86:89]
	v_lshl_or_b32 v1, v142, 2, v1
	s_lshl_b32 s16, s16, 1
	s_ashr_i32 s17, s16, 31
	v_mfma_f32_16x16x32_bf16 v[54:57], v[158:161], v[162:165], v[54:57]
	s_lshl_b64 s[16:17], s[16:17], 2
	s_add_i32 s24, s24, 1
	v_mfma_f32_16x16x32_bf16 v[122:125], v[130:133], v[166:169], v[122:125]
	v_mfma_f32_16x16x32_bf16 v[102:105], v[134:137], v[166:169], v[102:105]
	v_mfma_f32_16x16x32_bf16 v[70:73], v[138:141], v[166:169], v[70:73]
	v_mfma_f32_16x16x32_bf16 v[38:41], v[158:161], v[166:169], v[38:41]
	v_mfma_f32_16x16x32_bf16 v[118:121], v[130:133], v[192:195], v[118:121]
	v_mfma_f32_16x16x32_bf16 v[90:93], v[134:137], v[192:195], v[90:93]
	v_mfma_f32_16x16x32_bf16 v[58:61], v[138:141], v[192:195], v[58:61]
	v_mfma_f32_16x16x32_bf16 v[26:29], v[158:161], v[192:195], v[26:29]
	v_mfma_f32_16x16x32_bf16 v[110:113], v[130:133], v[196:199], v[110:113]
	v_mfma_f32_16x16x32_bf16 v[78:81], v[134:137], v[196:199], v[78:81]
	v_mfma_f32_16x16x32_bf16 v[46:49], v[138:141], v[196:199], v[46:49]
	v_mfma_f32_16x16x32_bf16 v[18:21], v[158:161], v[196:199], v[18:21]
	v_mfma_f32_16x16x32_bf16 v[106:109], v[130:133], v[200:203], v[106:109]
	v_mfma_f32_16x16x32_bf16 v[74:77], v[134:137], v[200:203], v[74:77]
	v_mfma_f32_16x16x32_bf16 v[42:45], v[138:141], v[200:203], v[42:45]
	v_mfma_f32_16x16x32_bf16 v[14:17], v[158:161], v[200:203], v[14:17]
	v_mfma_f32_16x16x32_bf16 v[98:101], v[130:133], v[204:207], v[98:101]
	v_mfma_f32_16x16x32_bf16 v[66:69], v[134:137], v[204:207], v[66:69]
	v_mfma_f32_16x16x32_bf16 v[34:37], v[138:141], v[204:207], v[34:37]
	v_mfma_f32_16x16x32_bf16 v[10:13], v[158:161], v[204:207], v[10:13]
	v_mfma_f32_16x16x32_bf16 v[94:97], v[130:133], v[208:211], v[94:97]
	v_mfma_f32_16x16x32_bf16 v[162:165], v[134:137], v[208:211], v[62:65]
	v_mfma_f32_16x16x32_bf16 v[166:169], v[138:141], v[208:211], v[30:33]
	v_mfma_f32_16x16x32_bf16 v[6:9], v[158:161], v[208:211], v[6:9]
	v_mfma_f32_16x16x32_bf16 v[82:85], v[130:133], v[212:215], v[82:85]
	v_mfma_f32_16x16x32_bf16 v[50:53], v[134:137], v[212:215], v[50:53]
	v_mfma_f32_16x16x32_bf16 v[130:133], v[138:141], v[212:215], v[22:25]
	v_mfma_f32_16x16x32_bf16 v[2:5], v[158:161], v[212:215], v[2:5]
	ds_read_b128 v[134:137], v145 offset:24576
	ds_read_b128 v[138:141], v145 offset:25600
	ds_read_b128 v[158:161], v145 offset:26624
	ds_read_b128 v[192:195], v145 offset:27648
	ds_read_b128 v[22:25], v144 offset:40960
	ds_read_b128 v[30:33], v144 offset:41984
	ds_read_b128 v[62:65], v144 offset:43008
	ds_read_b128 v[196:199], v144 offset:44032
	ds_read_b128 v[200:203], v144 offset:45056
	ds_read_b128 v[204:207], v144 offset:46080
	ds_read_b128 v[208:211], v144 offset:47104
	ds_read_b128 v[212:215], v144 offset:48128
	s_waitcnt lgkmcnt(0)
	v_mfma_f32_16x16x32_bf16 v[232:235], v[192:195], v[30:33], v[38:41]
	v_mfma_f32_16x16x32_bf16 v[38:41], v[158:161], v[204:207], v[34:37]
	v_mfma_f32_16x16x32_bf16 v[34:37], v[192:195], v[212:215], v[2:5]
	s_nop 2
	v_mov_b32_e32 v2, v170
	v_mfma_f32_16x16x32_bf16 v[216:219], v[138:141], v[22:25], v[114:117]
	v_add_u32_e32 v2, s4, v2
	v_ashrrev_i32_e32 v3, 31, v2
	v_lshlrev_b64 v[2:3], 11, v[2:3]
	v_lshl_add_u64 v[2:3], s[8:9], 0, v[2:3]
	v_lshl_add_u64 v[2:3], v[2:3], 0, s[18:19]
	v_mfma_f32_16x16x32_bf16 v[220:223], v[192:195], v[22:25], v[54:57]
	v_mfma_f32_16x16x32_bf16 v[224:227], v[134:137], v[30:33], v[122:125]
	v_mfma_f32_16x16x32_bf16 v[228:231], v[138:141], v[30:33], v[102:105]
	v_mfma_f32_16x16x32_bf16 v[236:239], v[134:137], v[62:65], v[118:121]
	v_mfma_f32_16x16x32_bf16 v[90:93], v[138:141], v[62:65], v[90:93]
	v_mfma_f32_16x16x32_bf16 v[240:243], v[158:161], v[62:65], v[58:61]
	v_mfma_f32_16x16x32_bf16 v[244:247], v[192:195], v[62:65], v[26:29]
	v_mfma_f32_16x16x32_bf16 v[248:251], v[134:137], v[196:199], v[110:113]
	v_mfma_f32_16x16x32_bf16 v[180:183], v[138:141], v[196:199], v[78:81]
	v_mfma_f32_16x16x32_bf16 v[154:157], v[158:161], v[196:199], v[46:49]
	v_mfma_f32_16x16x32_bf16 v[62:65], v[134:137], v[200:203], v[106:109]
	v_mfma_f32_16x16x32_bf16 v[46:49], v[138:141], v[200:203], v[74:77]
	v_mfma_f32_16x16x32_bf16 v[74:77], v[134:137], v[204:207], v[98:101]
	v_mfma_f32_16x16x32_bf16 v[54:57], v[138:141], v[204:207], v[66:69]
	v_mfma_f32_16x16x32_bf16 v[58:61], v[138:141], v[208:211], v[162:165]
	v_mfma_f32_16x16x32_bf16 v[66:69], v[138:141], v[212:215], v[50:53]
	flat_load_dwordx4 v[138:141], v[2:3]
	flat_load_dwordx4 v[122:125], v[2:3] offset:16
	flat_load_dwordx4 v[118:121], v[2:3] offset:32
	flat_load_dwordx4 v[114:117], v[2:3] offset:48
	flat_load_dwordx4 v[110:113], v[2:3] offset:64
	flat_load_dwordx4 v[106:109], v[2:3] offset:80
	flat_load_dwordx4 v[102:105], v[2:3] offset:96
	flat_load_dwordx4 v[98:101], v[2:3] offset:112
	s_waitcnt vmcnt(0) lgkmcnt(0)
	s_barrier
	v_mfma_f32_16x16x32_bf16 v[126:129], v[134:137], v[22:25], v[126:129]
	s_nop 7
	ds_write2_b32 v1, v126, v224 offset1:16
	ds_write2_b32 v1, v127, v225 offset0:68 offset1:84
	ds_write2_b32 v1, v128, v226 offset0:136 offset1:152
	ds_write2_b32 v1, v129, v227 offset0:204 offset1:220
	ds_write2_b32 v1, v236, v248 offset0:32 offset1:48
	ds_write2_b32 v1, v237, v249 offset0:100 offset1:116
	ds_write2_b32 v1, v238, v250 offset0:168 offset1:184
	ds_write2_b32 v1, v239, v251 offset0:236 offset1:252
	v_mfma_f32_16x16x32_bf16 v[86:89], v[158:161], v[22:25], v[86:89]
	v_mfma_f32_16x16x32_bf16 v[70:73], v[158:161], v[30:33], v[70:73]
	v_mfma_f32_16x16x32_bf16 v[196:199], v[192:195], v[196:199], v[18:21]
	v_mfma_f32_16x16x32_bf16 v[78:81], v[134:137], v[208:211], v[94:97]
	v_mfma_f32_16x16x32_bf16 v[82:85], v[134:137], v[212:215], v[82:85]
	v_add_u32_e32 v135, 0x3000, v1
	v_add_u32_e32 v134, 0x3400, v1
	v_mov_b32_e32 v136, v170
	v_mfma_f32_16x16x32_bf16 v[50:53], v[158:161], v[212:215], v[130:133]
	v_lshlrev_b32_e32 v137, 16, v138
	s_nop 1
	v_add_u32_e32 v130, 0x1000, v1
	v_add_u32_e32 v131, 0x1400, v1
	v_add_u32_e32 v132, 0x2000, v1
	v_add_u32_e32 v133, 0x2400, v1
	ds_write2_b32 v130, v216, v228 offset0:64 offset1:80
	ds_write2_b32 v130, v217, v229 offset0:132 offset1:148
	ds_write2_b32 v130, v218, v230 offset0:200 offset1:216
	ds_write2_b32 v131, v219, v231 offset0:12 offset1:28
	ds_write2_b32 v130, v90, v180 offset0:96 offset1:112
	ds_write2_b32 v130, v91, v181 offset0:164 offset1:180
	ds_write2_b32 v130, v92, v182 offset0:232 offset1:248
	ds_write2_b32 v131, v93, v183 offset0:44 offset1:60
	ds_write2_b32 v132, v86, v70 offset0:128 offset1:144
	ds_write2_b32 v132, v87, v71 offset0:196 offset1:212
	ds_write2_b32 v133, v88, v72 offset0:8 offset1:24
	ds_write2_b32 v133, v89, v73 offset0:76 offset1:92
	ds_write2_b32 v132, v240, v154 offset0:160 offset1:176
	ds_write2_b32 v132, v241, v155 offset0:228 offset1:244
	ds_write2_b32 v133, v242, v156 offset0:40 offset1:56
	ds_write2_b32 v133, v243, v157 offset0:108 offset1:124
	ds_write2_b32 v135, v220, v232 offset0:192 offset1:208
	ds_write2_b32 v134, v221, v233 offset0:4 offset1:20
	ds_write2_b32 v134, v222, v234 offset0:72 offset1:88
	ds_write2_b32 v134, v223, v235 offset0:140 offset1:156
	ds_write2_b32 v135, v244, v196 offset0:224 offset1:240
	ds_write2_b32 v134, v245, v197 offset0:36 offset1:52
	ds_write2_b32 v134, v246, v198 offset0:104 offset1:120
	ds_write2_b32 v134, v247, v199 offset0:172 offset1:188
	s_waitcnt lgkmcnt(0)
	s_barrier
	v_mfma_f32_16x16x32_bf16 v[18:21], v[192:195], v[200:203], v[14:17]
	v_add_u32_e32 v126, s4, v136
	v_ashrrev_i32_e32 v127, 31, v126
	v_lshlrev_b64 v[2:3], 11, v[126:127]
	v_lshl_add_u64 v[2:3], s[8:9], 0, v[2:3]
	v_lshl_add_u64 v[128:129], v[2:3], 0, s[18:19]
	v_mul_lo_u32 v136, v136, s33
	v_mfma_f32_16x16x32_bf16 v[22:25], v[192:195], v[204:207], v[10:13]
	v_and_b32_e32 v138, 0xffff0000, v138
	v_mfma_f32_16x16x32_bf16 v[26:29], v[192:195], v[208:211], v[6:9]
	flat_load_dwordx4 v[94:97], v[128:129] offset:128
	flat_load_dwordx4 v[90:93], v[128:129] offset:144
	flat_load_dwordx4 v[86:89], v[128:129] offset:160
	flat_load_dwordx4 v[70:73], v[128:129] offset:176
	flat_load_dwordx4 v[14:17], v[128:129] offset:192
	flat_load_dwordx4 v[10:13], v[128:129] offset:208
	flat_load_dwordx4 v[6:9], v[128:129] offset:224
	flat_load_dwordx4 v[2:5], v[128:129] offset:240
	ds_read_b128 v[142:145], v136
	ds_read_b128 v[154:157], v136 offset:16
	s_waitcnt lgkmcnt(0)
	v_add_f32_e32 v137, v142, v137
	v_add_f32_e32 v138, v143, v138
	v_cvt_pk_bf16_f32 v138, v137, v138
	v_lshlrev_b32_e32 v137, 16, v139
	v_and_b32_e32 v139, 0xffff0000, v139
	v_add_f32_e32 v137, v144, v137
	v_add_f32_e32 v139, v145, v139
	v_cvt_pk_bf16_f32 v139, v137, v139
	v_lshlrev_b32_e32 v137, 16, v140
	v_and_b32_e32 v140, 0xffff0000, v140
	v_add_f32_e32 v137, v154, v137
	v_add_f32_e32 v140, v155, v140
	v_cvt_pk_bf16_f32 v140, v137, v140
	v_lshlrev_b32_e32 v137, 16, v141
	v_and_b32_e32 v141, 0xffff0000, v141
	v_add_f32_e32 v137, v156, v137
	v_add_f32_e32 v141, v157, v141
	v_and_b32_e32 v142, 0xffff0000, v138
	v_cvt_pk_bf16_f32 v141, v137, v141
	v_lshlrev_b32_e32 v137, 16, v138
	v_mul_f32_e32 v153, v142, v142
	v_lshlrev_b32_e32 v143, 16, v139
	v_fmac_f32_e32 v153, v137, v137
	v_and_b32_e32 v144, 0xffff0000, v139
	v_fmac_f32_e32 v153, v143, v143
	v_lshlrev_b32_e32 v145, 16, v140
	v_fmac_f32_e32 v153, v144, v144
	flat_store_dwordx4 v[128:129], v[138:141]
	v_and_b32_e32 v147, 0xffff0000, v140
	v_lshlrev_b32_e32 v149, 16, v141
	v_and_b32_e32 v151, 0xffff0000, v141
	v_fmac_f32_e32 v153, v145, v145
	ds_read_b128 v[138:141], v136 offset:32
	ds_read_b128 v[142:145], v136 offset:48
	v_lshlrev_b32_e32 v137, 16, v122
	v_and_b32_e32 v122, 0xffff0000, v122
	v_fmac_f32_e32 v153, v147, v147
	s_waitcnt lgkmcnt(0)
	v_add_f32_e32 v137, v138, v137
	v_add_f32_e32 v122, v139, v122
	v_cvt_pk_bf16_f32 v122, v137, v122
	v_lshlrev_b32_e32 v137, 16, v123
	v_and_b32_e32 v123, 0xffff0000, v123
	v_add_f32_e32 v137, v140, v137
	v_add_f32_e32 v123, v141, v123
	v_cvt_pk_bf16_f32 v123, v137, v123
	v_lshlrev_b32_e32 v137, 16, v124
	v_and_b32_e32 v124, 0xffff0000, v124
	v_add_f32_e32 v137, v142, v137
	v_add_f32_e32 v124, v143, v124
	v_cvt_pk_bf16_f32 v124, v137, v124
	v_lshlrev_b32_e32 v137, 16, v125
	v_and_b32_e32 v125, 0xffff0000, v125
	v_add_f32_e32 v137, v144, v137
	v_add_f32_e32 v125, v145, v125
	v_and_b32_e32 v138, 0xffff0000, v122
	v_cvt_pk_bf16_f32 v125, v137, v125
	v_lshlrev_b32_e32 v137, 16, v122
	v_mul_f32_e32 v138, v138, v138
	v_lshlrev_b32_e32 v139, 16, v123
	v_fmac_f32_e32 v138, v137, v137
	v_and_b32_e32 v140, 0xffff0000, v123
	v_fmac_f32_e32 v138, v139, v139
	v_lshlrev_b32_e32 v141, 16, v124
	v_fmac_f32_e32 v138, v140, v140
	v_and_b32_e32 v142, 0xffff0000, v124
	v_fmac_f32_e32 v138, v141, v141
	v_lshlrev_b32_e32 v143, 16, v125
	v_fmac_f32_e32 v138, v142, v142
	v_fmac_f32_e32 v153, v149, v149
	v_and_b32_e32 v144, 0xffff0000, v125
	v_fmac_f32_e32 v138, v143, v143
	v_fmac_f32_e32 v153, v151, v151
	v_fmac_f32_e32 v138, v144, v144
	flat_store_dwordx4 v[128:129], v[122:125] offset:16
	v_add_f32_e32 v137, v153, v138
	ds_read_b128 v[122:125], v136 offset:64
	ds_read_b128 v[138:141], v136 offset:80
	v_lshlrev_b32_e32 v142, 16, v118
	v_and_b32_e32 v118, 0xffff0000, v118
	v_mfma_f32_16x16x32_bf16 v[30:33], v[158:161], v[200:203], v[42:45]
	s_waitcnt lgkmcnt(0)
	v_add_f32_e32 v122, v122, v142
	v_add_f32_e32 v118, v123, v118
	v_cvt_pk_bf16_f32 v118, v122, v118
	v_lshlrev_b32_e32 v122, 16, v119
	v_and_b32_e32 v119, 0xffff0000, v119
	v_add_f32_e32 v122, v124, v122
	v_add_f32_e32 v119, v125, v119
	v_cvt_pk_bf16_f32 v119, v122, v119
	v_lshlrev_b32_e32 v122, 16, v120
	v_and_b32_e32 v120, 0xffff0000, v120
	v_add_f32_e32 v122, v138, v122
	v_add_f32_e32 v120, v139, v120
	v_cvt_pk_bf16_f32 v120, v122, v120
	v_lshlrev_b32_e32 v122, 16, v121
	v_and_b32_e32 v121, 0xffff0000, v121
	v_add_f32_e32 v122, v140, v122
	v_add_f32_e32 v121, v141, v121
	v_and_b32_e32 v123, 0xffff0000, v118
	v_cvt_pk_bf16_f32 v121, v122, v121
	v_lshlrev_b32_e32 v122, 16, v118
	v_mul_f32_e32 v123, v123, v123
	v_lshlrev_b32_e32 v124, 16, v119
	v_fmac_f32_e32 v123, v122, v122
	v_and_b32_e32 v125, 0xffff0000, v119
	v_fmac_f32_e32 v123, v124, v124
	v_lshlrev_b32_e32 v138, 16, v120
	v_fmac_f32_e32 v123, v125, v125
	v_and_b32_e32 v139, 0xffff0000, v120
	v_fmac_f32_e32 v123, v138, v138
	v_lshlrev_b32_e32 v140, 16, v121
	v_fmac_f32_e32 v123, v139, v139
	v_and_b32_e32 v141, 0xffff0000, v121
	v_fmac_f32_e32 v123, v140, v140
	v_fmac_f32_e32 v123, v141, v141
	flat_store_dwordx4 v[128:129], v[118:121] offset:32
	v_add_f32_e32 v137, v137, v123
	ds_read_b128 v[118:121], v136 offset:96
	ds_read_b128 v[122:125], v136 offset:112
	v_lshlrev_b32_e32 v138, 16, v114
	v_and_b32_e32 v114, 0xffff0000, v114
	v_mfma_f32_16x16x32_bf16 v[42:45], v[158:161], v[208:211], v[166:169]
	s_waitcnt lgkmcnt(0)
	v_add_f32_e32 v118, v118, v138
	v_add_f32_e32 v114, v119, v114
	v_cvt_pk_bf16_f32 v114, v118, v114
	v_lshlrev_b32_e32 v118, 16, v115
	v_and_b32_e32 v115, 0xffff0000, v115
	v_add_f32_e32 v118, v120, v118
	v_add_f32_e32 v115, v121, v115
	v_cvt_pk_bf16_f32 v115, v118, v115
	v_lshlrev_b32_e32 v118, 16, v116
	v_and_b32_e32 v116, 0xffff0000, v116
	v_add_f32_e32 v118, v122, v118
	v_add_f32_e32 v116, v123, v116
	v_cvt_pk_bf16_f32 v116, v118, v116
	v_lshlrev_b32_e32 v118, 16, v117
	v_and_b32_e32 v117, 0xffff0000, v117
	v_add_f32_e32 v118, v124, v118
	v_add_f32_e32 v117, v125, v117
	v_and_b32_e32 v119, 0xffff0000, v114
	v_cvt_pk_bf16_f32 v117, v118, v117
	v_lshlrev_b32_e32 v118, 16, v114
	v_mul_f32_e32 v119, v119, v119
	v_lshlrev_b32_e32 v120, 16, v115
	v_fmac_f32_e32 v119, v118, v118
	v_and_b32_e32 v121, 0xffff0000, v115
	v_fmac_f32_e32 v119, v120, v120
	v_lshlrev_b32_e32 v122, 16, v116
	v_fmac_f32_e32 v119, v121, v121
	v_and_b32_e32 v123, 0xffff0000, v116
	v_fmac_f32_e32 v119, v122, v122
	v_lshlrev_b32_e32 v124, 16, v117
	v_fmac_f32_e32 v119, v123, v123
	v_and_b32_e32 v125, 0xffff0000, v117
	v_fmac_f32_e32 v119, v124, v124
	v_fmac_f32_e32 v119, v125, v125
	flat_store_dwordx4 v[128:129], v[114:117] offset:48
	v_add_f32_e32 v122, v137, v119
	ds_read_b128 v[114:117], v136 offset:128
	ds_read_b128 v[118:121], v136 offset:144
	v_lshlrev_b32_e32 v123, 16, v110
	v_and_b32_e32 v110, 0xffff0000, v110
	s_waitcnt lgkmcnt(0)
	v_add_f32_e32 v114, v114, v123
	v_add_f32_e32 v110, v115, v110
	v_cvt_pk_bf16_f32 v110, v114, v110
	v_lshlrev_b32_e32 v114, 16, v111
	v_and_b32_e32 v111, 0xffff0000, v111
	v_add_f32_e32 v114, v116, v114
	v_add_f32_e32 v111, v117, v111
	v_cvt_pk_bf16_f32 v111, v114, v111
	v_lshlrev_b32_e32 v114, 16, v112
	v_and_b32_e32 v112, 0xffff0000, v112
	v_add_f32_e32 v114, v118, v114
	v_add_f32_e32 v112, v119, v112
	v_cvt_pk_bf16_f32 v112, v114, v112
	v_lshlrev_b32_e32 v114, 16, v113
	v_and_b32_e32 v113, 0xffff0000, v113
	v_add_f32_e32 v114, v120, v114
	v_add_f32_e32 v113, v121, v113
	v_and_b32_e32 v115, 0xffff0000, v110
	v_cvt_pk_bf16_f32 v113, v114, v113
	v_lshlrev_b32_e32 v114, 16, v110
	v_mul_f32_e32 v115, v115, v115
	v_lshlrev_b32_e32 v116, 16, v111
	v_fmac_f32_e32 v115, v114, v114
	v_and_b32_e32 v117, 0xffff0000, v111
	v_fmac_f32_e32 v115, v116, v116
	v_lshlrev_b32_e32 v118, 16, v112
	v_fmac_f32_e32 v115, v117, v117
	v_and_b32_e32 v119, 0xffff0000, v112
	v_fmac_f32_e32 v115, v118, v118
	v_lshlrev_b32_e32 v120, 16, v113
	v_fmac_f32_e32 v115, v119, v119
	v_and_b32_e32 v121, 0xffff0000, v113
	v_fmac_f32_e32 v115, v120, v120
	v_fmac_f32_e32 v115, v121, v121
	flat_store_dwordx4 v[128:129], v[110:113] offset:64
	v_add_f32_e32 v118, v122, v115
	ds_read_b128 v[110:113], v136 offset:160
	ds_read_b128 v[114:117], v136 offset:176
	v_lshlrev_b32_e32 v119, 16, v106
	v_and_b32_e32 v106, 0xffff0000, v106
	s_waitcnt lgkmcnt(0)
	v_add_f32_e32 v110, v110, v119
	v_add_f32_e32 v106, v111, v106
	v_cvt_pk_bf16_f32 v106, v110, v106
	v_lshlrev_b32_e32 v110, 16, v107
	v_and_b32_e32 v107, 0xffff0000, v107
	v_add_f32_e32 v110, v112, v110
	v_add_f32_e32 v107, v113, v107
	v_cvt_pk_bf16_f32 v107, v110, v107
	v_lshlrev_b32_e32 v110, 16, v108
	v_and_b32_e32 v108, 0xffff0000, v108
	v_add_f32_e32 v110, v114, v110
	v_add_f32_e32 v108, v115, v108
	v_cvt_pk_bf16_f32 v108, v110, v108
	v_lshlrev_b32_e32 v110, 16, v109
	v_and_b32_e32 v109, 0xffff0000, v109
	v_add_f32_e32 v110, v116, v110
	v_add_f32_e32 v109, v117, v109
	v_and_b32_e32 v111, 0xffff0000, v106
	v_cvt_pk_bf16_f32 v109, v110, v109
	v_lshlrev_b32_e32 v110, 16, v106
	v_mul_f32_e32 v111, v111, v111
	v_lshlrev_b32_e32 v112, 16, v107
	v_fmac_f32_e32 v111, v110, v110
	v_and_b32_e32 v113, 0xffff0000, v107
	v_fmac_f32_e32 v111, v112, v112
	v_lshlrev_b32_e32 v114, 16, v108
	v_fmac_f32_e32 v111, v113, v113
	v_and_b32_e32 v115, 0xffff0000, v108
	v_fmac_f32_e32 v111, v114, v114
	v_lshlrev_b32_e32 v116, 16, v109
	v_fmac_f32_e32 v111, v115, v115
	v_and_b32_e32 v117, 0xffff0000, v109
	v_fmac_f32_e32 v111, v116, v116
	v_fmac_f32_e32 v111, v117, v117
	flat_store_dwordx4 v[128:129], v[106:109] offset:80
	v_add_f32_e32 v114, v118, v111
	ds_read_b128 v[106:109], v136 offset:192
	ds_read_b128 v[110:113], v136 offset:208
	v_lshlrev_b32_e32 v115, 16, v102
	v_and_b32_e32 v102, 0xffff0000, v102
	s_waitcnt lgkmcnt(0)
	v_add_f32_e32 v106, v106, v115
	v_add_f32_e32 v102, v107, v102
	v_cvt_pk_bf16_f32 v102, v106, v102
	v_lshlrev_b32_e32 v106, 16, v103
	v_and_b32_e32 v103, 0xffff0000, v103
	v_add_f32_e32 v106, v108, v106
	v_add_f32_e32 v103, v109, v103
	v_cvt_pk_bf16_f32 v103, v106, v103
	v_lshlrev_b32_e32 v106, 16, v104
	v_and_b32_e32 v104, 0xffff0000, v104
	v_add_f32_e32 v106, v110, v106
	v_add_f32_e32 v104, v111, v104
	v_cvt_pk_bf16_f32 v104, v106, v104
	v_lshlrev_b32_e32 v106, 16, v105
	v_and_b32_e32 v105, 0xffff0000, v105
	v_add_f32_e32 v106, v112, v106
	v_add_f32_e32 v105, v113, v105
	v_and_b32_e32 v107, 0xffff0000, v102
	v_cvt_pk_bf16_f32 v105, v106, v105
	v_lshlrev_b32_e32 v106, 16, v102
	v_mul_f32_e32 v107, v107, v107
	v_lshlrev_b32_e32 v108, 16, v103
	v_fmac_f32_e32 v107, v106, v106
	v_and_b32_e32 v109, 0xffff0000, v103
	v_fmac_f32_e32 v107, v108, v108
	v_lshlrev_b32_e32 v110, 16, v104
	v_fmac_f32_e32 v107, v109, v109
	v_and_b32_e32 v111, 0xffff0000, v104
	v_fmac_f32_e32 v107, v110, v110
	v_lshlrev_b32_e32 v112, 16, v105
	v_fmac_f32_e32 v107, v111, v111
	v_and_b32_e32 v113, 0xffff0000, v105
	v_fmac_f32_e32 v107, v112, v112
	v_fmac_f32_e32 v107, v113, v113
	flat_store_dwordx4 v[128:129], v[102:105] offset:96
	v_add_f32_e32 v110, v114, v107
	ds_read_b128 v[102:105], v136 offset:224
	ds_read_b128 v[106:109], v136 offset:240
	v_lshlrev_b32_e32 v111, 16, v98
	v_and_b32_e32 v98, 0xffff0000, v98
	s_waitcnt lgkmcnt(0)
	v_add_f32_e32 v102, v102, v111
	v_add_f32_e32 v98, v103, v98
	v_cvt_pk_bf16_f32 v98, v102, v98
	v_lshlrev_b32_e32 v102, 16, v99
	v_and_b32_e32 v99, 0xffff0000, v99
	v_add_f32_e32 v102, v104, v102
	v_add_f32_e32 v99, v105, v99
	v_cvt_pk_bf16_f32 v99, v102, v99
	v_lshlrev_b32_e32 v102, 16, v100
	v_and_b32_e32 v100, 0xffff0000, v100
	v_add_f32_e32 v102, v106, v102
	v_add_f32_e32 v100, v107, v100
	v_cvt_pk_bf16_f32 v100, v102, v100
	v_lshlrev_b32_e32 v102, 16, v101
	v_and_b32_e32 v101, 0xffff0000, v101
	v_add_f32_e32 v102, v108, v102
	v_add_f32_e32 v101, v109, v101
	v_and_b32_e32 v103, 0xffff0000, v98
	v_cvt_pk_bf16_f32 v101, v102, v101
	v_lshlrev_b32_e32 v102, 16, v98
	v_mul_f32_e32 v103, v103, v103
	v_lshlrev_b32_e32 v104, 16, v99
	v_fmac_f32_e32 v103, v102, v102
	v_and_b32_e32 v105, 0xffff0000, v99
	v_fmac_f32_e32 v103, v104, v104
	v_lshlrev_b32_e32 v106, 16, v100
	v_fmac_f32_e32 v103, v105, v105
	v_and_b32_e32 v107, 0xffff0000, v100
	v_fmac_f32_e32 v103, v106, v106
	v_lshlrev_b32_e32 v108, 16, v101
	v_fmac_f32_e32 v103, v107, v107
	v_and_b32_e32 v109, 0xffff0000, v101
	v_fmac_f32_e32 v103, v108, v108
	flat_store_dwordx4 v[128:129], v[98:101] offset:112
	v_fmac_f32_e32 v103, v109, v109
	v_add_f32_e32 v102, v110, v103
	v_lshlrev_b64 v[98:99], 6, v[126:127]
	v_lshl_add_u64 v[98:99], s[6:7], 0, v[98:99]
	v_lshl_add_u64 v[98:99], v[98:99], 0, s[16:17]
	flat_store_dword v[98:99], v102
	s_waitcnt lgkmcnt(0)
	s_barrier
	ds_write2_b32 v1, v62, v74 offset1:16
	ds_write2_b32 v1, v63, v75 offset0:68 offset1:84
	ds_write2_b32 v1, v64, v76 offset0:136 offset1:152
	ds_write2_b32 v1, v65, v77 offset0:204 offset1:220
	ds_write2_b32 v1, v78, v82 offset0:32 offset1:48
	ds_write2_b32 v1, v79, v83 offset0:100 offset1:116
	ds_write2_b32 v1, v80, v84 offset0:168 offset1:184
	ds_write2_b32 v1, v81, v85 offset0:236 offset1:252
	ds_write2_b32 v130, v46, v54 offset0:64 offset1:80
	ds_write2_b32 v130, v47, v55 offset0:132 offset1:148
	ds_write2_b32 v130, v48, v56 offset0:200 offset1:216
	ds_write2_b32 v131, v49, v57 offset0:12 offset1:28
	ds_write2_b32 v130, v58, v66 offset0:96 offset1:112
	ds_write2_b32 v130, v59, v67 offset0:164 offset1:180
	ds_write2_b32 v130, v60, v68 offset0:232 offset1:248
	ds_write2_b32 v131, v61, v69 offset0:44 offset1:60
	ds_write2_b32 v132, v30, v38 offset0:128 offset1:144
	ds_write2_b32 v132, v31, v39 offset0:196 offset1:212
	ds_write2_b32 v133, v32, v40 offset0:8 offset1:24
	ds_write2_b32 v133, v33, v41 offset0:76 offset1:92
	ds_write2_b32 v132, v42, v50 offset0:160 offset1:176
	ds_write2_b32 v132, v43, v51 offset0:228 offset1:244
	ds_write2_b32 v133, v44, v52 offset0:40 offset1:56
	ds_write2_b32 v133, v45, v53 offset0:108 offset1:124
	ds_write2_b32 v135, v18, v22 offset0:192 offset1:208
	ds_write2_b32 v134, v19, v23 offset0:4 offset1:20
	ds_write2_b32 v134, v20, v24 offset0:72 offset1:88
	ds_write2_b32 v134, v21, v25 offset0:140 offset1:156
	ds_write2_b32 v135, v26, v34 offset0:224 offset1:240
	ds_write2_b32 v134, v27, v35 offset0:36 offset1:52
	ds_write2_b32 v134, v28, v36 offset0:104 offset1:120
	ds_write2_b32 v134, v29, v37 offset0:172 offset1:188
	v_mov_b32_e32 v1, v170
	s_waitcnt lgkmcnt(0)
	s_barrier
	s_waitcnt vmcnt(0)
	v_lshlrev_b32_e32 v28, 16, v94
	v_add_u32_e32 v18, s4, v1
	v_ashrrev_i32_e32 v19, 31, v18
	v_lshlrev_b64 v[20:21], 11, v[18:19]
	v_lshl_add_u64 v[20:21], s[38:39], 0, v[20:21]
	v_mul_lo_u32 v1, v1, s33
	v_lshl_add_u64 v[32:33], v[20:21], 0, s[18:19]
	ds_read_b128 v[20:23], v1
	ds_read_b128 v[24:27], v1 offset:16
	s_mov_b64 s[4:5], 0
	s_waitcnt lgkmcnt(1)
	v_add_f32_e32 v20, v20, v28
	v_and_b32_e32 v28, 0xffff0000, v94
	v_add_f32_e32 v21, v21, v28
	v_cvt_pk_bf16_f32 v28, v20, v21
	v_and_b32_e32 v21, 0xffff0000, v95
	v_lshlrev_b32_e32 v20, 16, v95
	v_add_f32_e32 v21, v23, v21
	v_add_f32_e32 v20, v22, v20
	v_cvt_pk_bf16_f32 v29, v20, v21
	v_and_b32_e32 v21, 0xffff0000, v96
	v_lshlrev_b32_e32 v20, 16, v96
	s_waitcnt lgkmcnt(0)
	v_add_f32_e32 v21, v25, v21
	v_add_f32_e32 v20, v24, v20
	v_cvt_pk_bf16_f32 v30, v20, v21
	v_and_b32_e32 v21, 0xffff0000, v97
	v_lshlrev_b32_e32 v20, 16, v97
	v_add_f32_e32 v21, v27, v21
	v_add_f32_e32 v20, v26, v20
	v_cvt_pk_bf16_f32 v31, v20, v21
	v_and_b32_e32 v21, 0xffff0000, v28
	v_lshlrev_b32_e32 v20, 16, v28
	v_mul_f32_e32 v34, v21, v21
	v_lshlrev_b32_e32 v22, 16, v29
	v_fmac_f32_e32 v34, v20, v20
	v_and_b32_e32 v23, 0xffff0000, v29
	v_fmac_f32_e32 v34, v22, v22
	v_lshlrev_b32_e32 v24, 16, v30
	v_fmac_f32_e32 v34, v23, v23
	v_and_b32_e32 v25, 0xffff0000, v30
	v_fmac_f32_e32 v34, v24, v24
	v_add_co_u32_e32 v20, vcc, s90, v32
	v_lshlrev_b32_e32 v26, 16, v31
	v_fmac_f32_e32 v34, v25, v25
	v_addc_co_u32_e32 v21, vcc, 0, v33, vcc
	v_and_b32_e32 v27, 0xffff0000, v31
	v_fmac_f32_e32 v34, v26, v26
	flat_store_dwordx4 v[20:21], v[28:31] offset:128
	v_fmac_f32_e32 v34, v27, v27
	ds_read_b128 v[22:25], v1 offset:32
	ds_read_b128 v[26:29], v1 offset:48
	v_lshlrev_b32_e32 v30, 16, v90
	s_waitcnt lgkmcnt(0)
	v_add_f32_e32 v22, v22, v30
	v_and_b32_e32 v30, 0xffff0000, v90
	v_add_f32_e32 v23, v23, v30
	v_cvt_pk_bf16_f32 v22, v22, v23
	v_lshlrev_b32_e32 v23, 16, v91
	v_add_f32_e32 v23, v24, v23
	v_and_b32_e32 v24, 0xffff0000, v91
	v_add_f32_e32 v24, v25, v24
	v_cvt_pk_bf16_f32 v23, v23, v24
	v_lshlrev_b32_e32 v24, 16, v92
	v_and_b32_e32 v25, 0xffff0000, v92
	v_add_f32_e32 v24, v26, v24
	v_add_f32_e32 v25, v27, v25
	v_cvt_pk_bf16_f32 v24, v24, v25
	v_lshlrev_b32_e32 v25, 16, v93
	v_and_b32_e32 v26, 0xffff0000, v93
	v_add_f32_e32 v25, v28, v25
	v_add_f32_e32 v26, v29, v26
	v_and_b32_e32 v27, 0xffff0000, v22
	v_cvt_pk_bf16_f32 v25, v25, v26
	v_lshlrev_b32_e32 v26, 16, v22
	v_mul_f32_e32 v27, v27, v27
	v_lshlrev_b32_e32 v28, 16, v23
	v_fmac_f32_e32 v27, v26, v26
	v_and_b32_e32 v29, 0xffff0000, v23
	v_fmac_f32_e32 v27, v28, v28
	v_lshlrev_b32_e32 v30, 16, v24
	v_fmac_f32_e32 v27, v29, v29
	v_and_b32_e32 v31, 0xffff0000, v24
	v_fmac_f32_e32 v27, v30, v30
	v_lshlrev_b32_e32 v32, 16, v25
	v_fmac_f32_e32 v27, v31, v31
	v_and_b32_e32 v33, 0xffff0000, v25
	v_fmac_f32_e32 v27, v32, v32
	v_fmac_f32_e32 v27, v33, v33
	flat_store_dwordx4 v[20:21], v[22:25] offset:144
	v_add_f32_e32 v30, v34, v27
	ds_read_b128 v[22:25], v1 offset:64
	ds_read_b128 v[26:29], v1 offset:80
	v_lshlrev_b32_e32 v31, 16, v86
	s_waitcnt lgkmcnt(0)
	v_add_f32_e32 v22, v22, v31
	v_and_b32_e32 v31, 0xffff0000, v86
	v_add_f32_e32 v23, v23, v31
	v_cvt_pk_bf16_f32 v22, v22, v23
	v_lshlrev_b32_e32 v23, 16, v87
	v_add_f32_e32 v23, v24, v23
	v_and_b32_e32 v24, 0xffff0000, v87
	v_add_f32_e32 v24, v25, v24
	v_cvt_pk_bf16_f32 v23, v23, v24
	v_lshlrev_b32_e32 v24, 16, v88
	v_and_b32_e32 v25, 0xffff0000, v88
	v_add_f32_e32 v24, v26, v24
	v_add_f32_e32 v25, v27, v25
	v_cvt_pk_bf16_f32 v24, v24, v25
	v_lshlrev_b32_e32 v25, 16, v89
	v_and_b32_e32 v26, 0xffff0000, v89
	v_add_f32_e32 v25, v28, v25
	v_add_f32_e32 v26, v29, v26
	v_and_b32_e32 v27, 0xffff0000, v22
	v_cvt_pk_bf16_f32 v25, v25, v26
	v_lshlrev_b32_e32 v26, 16, v22
	v_mul_f32_e32 v27, v27, v27
	v_lshlrev_b32_e32 v28, 16, v23
	v_fmac_f32_e32 v27, v26, v26
	v_and_b32_e32 v29, 0xffff0000, v23
	v_fmac_f32_e32 v27, v28, v28
	v_lshlrev_b32_e32 v31, 16, v24
	v_fmac_f32_e32 v27, v29, v29
	v_and_b32_e32 v32, 0xffff0000, v24
	v_fmac_f32_e32 v27, v31, v31
	v_lshlrev_b32_e32 v33, 16, v25
	v_fmac_f32_e32 v27, v32, v32
	v_and_b32_e32 v34, 0xffff0000, v25
	v_fmac_f32_e32 v27, v33, v33
	v_fmac_f32_e32 v27, v34, v34
	flat_store_dwordx4 v[20:21], v[22:25] offset:160
	v_add_f32_e32 v30, v30, v27
	ds_read_b128 v[22:25], v1 offset:96
	ds_read_b128 v[26:29], v1 offset:112
	v_lshlrev_b32_e32 v31, 16, v70
	s_waitcnt lgkmcnt(0)
	v_add_f32_e32 v22, v22, v31
	v_and_b32_e32 v31, 0xffff0000, v70
	v_add_f32_e32 v23, v23, v31
	v_cvt_pk_bf16_f32 v22, v22, v23
	v_lshlrev_b32_e32 v23, 16, v71
	v_add_f32_e32 v23, v24, v23
	v_and_b32_e32 v24, 0xffff0000, v71
	v_add_f32_e32 v24, v25, v24
	v_cvt_pk_bf16_f32 v23, v23, v24
	v_lshlrev_b32_e32 v24, 16, v72
	v_and_b32_e32 v25, 0xffff0000, v72
	v_add_f32_e32 v24, v26, v24
	v_add_f32_e32 v25, v27, v25
	v_cvt_pk_bf16_f32 v24, v24, v25
	v_lshlrev_b32_e32 v25, 16, v73
	v_and_b32_e32 v26, 0xffff0000, v73
	v_add_f32_e32 v25, v28, v25
	v_add_f32_e32 v26, v29, v26
	v_and_b32_e32 v27, 0xffff0000, v22
	v_cvt_pk_bf16_f32 v25, v25, v26
	v_lshlrev_b32_e32 v26, 16, v22
	v_mul_f32_e32 v27, v27, v27
	v_lshlrev_b32_e32 v28, 16, v23
	v_fmac_f32_e32 v27, v26, v26
	v_and_b32_e32 v29, 0xffff0000, v23
	v_fmac_f32_e32 v27, v28, v28
	v_lshlrev_b32_e32 v31, 16, v24
	v_fmac_f32_e32 v27, v29, v29
	v_and_b32_e32 v32, 0xffff0000, v24
	v_fmac_f32_e32 v27, v31, v31
	v_lshlrev_b32_e32 v33, 16, v25
	v_fmac_f32_e32 v27, v32, v32
	v_and_b32_e32 v34, 0xffff0000, v25
	v_fmac_f32_e32 v27, v33, v33
	v_fmac_f32_e32 v27, v34, v34
	flat_store_dwordx4 v[20:21], v[22:25] offset:176
	v_add_f32_e32 v30, v30, v27
	ds_read_b128 v[22:25], v1 offset:128
	ds_read_b128 v[26:29], v1 offset:144
	v_lshlrev_b32_e32 v31, 16, v14
	v_and_b32_e32 v14, 0xffff0000, v14
	s_waitcnt lgkmcnt(0)
	v_add_f32_e32 v22, v22, v31
	v_add_f32_e32 v14, v23, v14
	v_cvt_pk_bf16_f32 v14, v22, v14
	v_lshlrev_b32_e32 v22, 16, v15
	v_and_b32_e32 v15, 0xffff0000, v15
	v_add_f32_e32 v22, v24, v22
	v_add_f32_e32 v15, v25, v15
	v_cvt_pk_bf16_f32 v15, v22, v15
	v_lshlrev_b32_e32 v22, 16, v16
	v_and_b32_e32 v16, 0xffff0000, v16
	v_add_f32_e32 v22, v26, v22
	v_add_f32_e32 v16, v27, v16
	v_cvt_pk_bf16_f32 v16, v22, v16
	v_lshlrev_b32_e32 v22, 16, v17
	v_and_b32_e32 v17, 0xffff0000, v17
	v_add_f32_e32 v22, v28, v22
	v_add_f32_e32 v17, v29, v17
	v_and_b32_e32 v23, 0xffff0000, v14
	v_cvt_pk_bf16_f32 v17, v22, v17
	v_lshlrev_b32_e32 v22, 16, v14
	v_mul_f32_e32 v23, v23, v23
	v_lshlrev_b32_e32 v24, 16, v15
	v_fmac_f32_e32 v23, v22, v22
	v_and_b32_e32 v25, 0xffff0000, v15
	v_fmac_f32_e32 v23, v24, v24
	v_lshlrev_b32_e32 v26, 16, v16
	v_fmac_f32_e32 v23, v25, v25
	v_and_b32_e32 v27, 0xffff0000, v16
	v_fmac_f32_e32 v23, v26, v26
	v_lshlrev_b32_e32 v28, 16, v17
	v_fmac_f32_e32 v23, v27, v27
	v_and_b32_e32 v29, 0xffff0000, v17
	v_fmac_f32_e32 v23, v28, v28
	v_fmac_f32_e32 v23, v29, v29
	flat_store_dwordx4 v[20:21], v[14:17] offset:192
	v_add_f32_e32 v26, v30, v23
	ds_read_b128 v[14:17], v1 offset:160
	ds_read_b128 v[22:25], v1 offset:176
	v_lshlrev_b32_e32 v27, 16, v10
	v_and_b32_e32 v10, 0xffff0000, v10
	s_waitcnt lgkmcnt(0)
	v_add_f32_e32 v14, v14, v27
	v_add_f32_e32 v10, v15, v10
	v_cvt_pk_bf16_f32 v10, v14, v10
	v_lshlrev_b32_e32 v14, 16, v11
	v_and_b32_e32 v11, 0xffff0000, v11
	v_add_f32_e32 v14, v16, v14
	v_add_f32_e32 v11, v17, v11
	v_cvt_pk_bf16_f32 v11, v14, v11
	v_lshlrev_b32_e32 v14, 16, v12
	v_and_b32_e32 v12, 0xffff0000, v12
	v_add_f32_e32 v14, v22, v14
	v_add_f32_e32 v12, v23, v12
	v_cvt_pk_bf16_f32 v12, v14, v12
	v_lshlrev_b32_e32 v14, 16, v13
	v_and_b32_e32 v13, 0xffff0000, v13
	v_add_f32_e32 v14, v24, v14
	v_add_f32_e32 v13, v25, v13
	v_and_b32_e32 v15, 0xffff0000, v10
	v_cvt_pk_bf16_f32 v13, v14, v13
	v_lshlrev_b32_e32 v14, 16, v10
	v_mul_f32_e32 v15, v15, v15
	v_lshlrev_b32_e32 v16, 16, v11
	v_fmac_f32_e32 v15, v14, v14
	v_and_b32_e32 v17, 0xffff0000, v11
	v_fmac_f32_e32 v15, v16, v16
	v_lshlrev_b32_e32 v22, 16, v12
	v_fmac_f32_e32 v15, v17, v17
	v_and_b32_e32 v23, 0xffff0000, v12
	v_fmac_f32_e32 v15, v22, v22
	v_lshlrev_b32_e32 v24, 16, v13
	v_fmac_f32_e32 v15, v23, v23
	v_and_b32_e32 v25, 0xffff0000, v13
	v_fmac_f32_e32 v15, v24, v24
	v_fmac_f32_e32 v15, v25, v25
	flat_store_dwordx4 v[20:21], v[10:13] offset:208
	v_add_f32_e32 v22, v26, v15
	ds_read_b128 v[10:13], v1 offset:192
	ds_read_b128 v[14:17], v1 offset:208
	v_lshlrev_b32_e32 v23, 16, v6
	v_and_b32_e32 v6, 0xffff0000, v6
	s_waitcnt lgkmcnt(0)
	v_add_f32_e32 v10, v10, v23
	v_add_f32_e32 v6, v11, v6
	v_cvt_pk_bf16_f32 v6, v10, v6
	v_lshlrev_b32_e32 v10, 16, v7
	v_and_b32_e32 v7, 0xffff0000, v7
	v_add_f32_e32 v10, v12, v10
	v_add_f32_e32 v7, v13, v7
	v_cvt_pk_bf16_f32 v7, v10, v7
	v_lshlrev_b32_e32 v10, 16, v8
	v_and_b32_e32 v8, 0xffff0000, v8
	v_add_f32_e32 v10, v14, v10
	v_add_f32_e32 v8, v15, v8
	v_cvt_pk_bf16_f32 v8, v10, v8
	v_lshlrev_b32_e32 v10, 16, v9
	v_and_b32_e32 v9, 0xffff0000, v9
	v_add_f32_e32 v10, v16, v10
	v_add_f32_e32 v9, v17, v9
	v_and_b32_e32 v11, 0xffff0000, v6
	v_cvt_pk_bf16_f32 v9, v10, v9
	v_lshlrev_b32_e32 v10, 16, v6
	v_mul_f32_e32 v11, v11, v11
	v_lshlrev_b32_e32 v12, 16, v7
	v_fmac_f32_e32 v11, v10, v10
	v_and_b32_e32 v13, 0xffff0000, v7
	v_fmac_f32_e32 v11, v12, v12
	v_lshlrev_b32_e32 v14, 16, v8
	v_fmac_f32_e32 v11, v13, v13
	v_and_b32_e32 v15, 0xffff0000, v8
	v_fmac_f32_e32 v11, v14, v14
	v_lshlrev_b32_e32 v16, 16, v9
	v_fmac_f32_e32 v11, v15, v15
	v_and_b32_e32 v17, 0xffff0000, v9
	v_fmac_f32_e32 v11, v16, v16
	v_fmac_f32_e32 v11, v17, v17
	flat_store_dwordx4 v[20:21], v[6:9] offset:224
	v_add_f32_e32 v14, v22, v11
	ds_read_b128 v[6:9], v1 offset:224
	ds_read_b128 v[10:13], v1 offset:240
	v_lshlrev_b32_e32 v1, 16, v2
	v_and_b32_e32 v2, 0xffff0000, v2
	s_waitcnt lgkmcnt(0)
	v_add_f32_e32 v1, v6, v1
	v_add_f32_e32 v2, v7, v2
	v_cvt_pk_bf16_f32 v2, v1, v2
	v_lshlrev_b32_e32 v1, 16, v3
	v_and_b32_e32 v3, 0xffff0000, v3
	v_add_f32_e32 v1, v8, v1
	v_add_f32_e32 v3, v9, v3
	v_cvt_pk_bf16_f32 v3, v1, v3
	v_lshlrev_b32_e32 v1, 16, v4
	v_and_b32_e32 v4, 0xffff0000, v4
	v_add_f32_e32 v1, v10, v1
	v_add_f32_e32 v4, v11, v4
	v_cvt_pk_bf16_f32 v4, v1, v4
	v_lshlrev_b32_e32 v1, 16, v5
	v_and_b32_e32 v5, 0xffff0000, v5
	v_add_f32_e32 v1, v12, v1
	v_add_f32_e32 v5, v13, v5
	v_and_b32_e32 v6, 0xffff0000, v2
	v_cvt_pk_bf16_f32 v5, v1, v5
	v_lshlrev_b32_e32 v1, 16, v2
	v_mul_f32_e32 v6, v6, v6
	v_lshlrev_b32_e32 v7, 16, v3
	v_fmac_f32_e32 v6, v1, v1
	v_and_b32_e32 v8, 0xffff0000, v3
	v_fmac_f32_e32 v6, v7, v7
	v_lshlrev_b32_e32 v9, 16, v4
	v_fmac_f32_e32 v6, v8, v8
	v_and_b32_e32 v10, 0xffff0000, v4
	v_fmac_f32_e32 v6, v9, v9
	v_lshlrev_b32_e32 v11, 16, v5
	v_fmac_f32_e32 v6, v10, v10
	v_and_b32_e32 v12, 0xffff0000, v5
	v_fmac_f32_e32 v6, v11, v11
	flat_store_dwordx4 v[20:21], v[2:5] offset:240
	v_fmac_f32_e32 v6, v12, v12
	v_add_f32_e32 v1, v14, v6
	v_lshlrev_b64 v[2:3], 6, v[18:19]
	v_lshl_add_u64 v[2:3], s[6:7], 0, v[2:3]
	v_lshl_add_u64 v[2:3], v[2:3], 0, s[16:17]
	flat_store_dword v[2:3], v1 offset:4
	s_branch .LBB0_522
